# planA: GU sample round overlapped with down prompt units via group counters; split-K on WGs 88..151
# speedup vs baseline: 1.0164x; 1.0164x over previous
; __device__ __forceinline__ unsigned xb_ld(unsigned* p)              { return __hip_atomic_load(p, __ATOMIC_RELAXED, __HIP_MEMORY_SCOPE_AGENT); }
;     __device__ __forceinline__ bool next(int i, Unit& u) const {
;         const long L = (long)i * G + c; if (L >= nwg) return false;
;         const int xcd = (int)(L % NXCD), off = (int)(L / NXCD), own = 8 * nN, grp = WGM * nN;
;         u.kb = 0;
;         if (off < own) { const int g2 = off / grp, idg = off - g2 * grp; u.pm = 8 * xcd + WGM * g2 + (idg % WGM); u.pn = (idg / WGM + xcd * ((nN + NXCD - 1) / NXCD)) % nN; }
;         else { const int q = nwg / NXCD, r = nwg % NXCD, id = xcd * (q - own) + (xcd < r ? xcd : r) + (off - own); u.pm = 64 + (id & 1); u.pn = id >> 1; }
; __device__ __forceinline__ void xcd_barrier_complete(unsigned* bar, unsigned x, unsigned& nloc, unsigned& nx) {
;     const unsigned G = gridDim.x * gridDim.y * gridDim.z;
;     unsigned sum, cnt, mine, sp = 0u;
;     for (;;) {
;         sum = 0u; cnt = 0u; mine = 0u;
; #pragma unroll
;         for (unsigned j = 0; j < 16; ++j) { const unsigned c = xb_ld(&bar[XB_XCNT(j)]); sum += c; cnt += (c > 0u) ? 1u : 0u; mine = (j == x) ? c : mine; }
;         if (sum == G) break;
;         __builtin_amdgcn_s_sleep(1);
;         if ((++sp & 255u) == 0u) { if (xb_ld(&bar[XB_TMO])) break; if (sp > XB_SPIN_CAP) { atomicAdd(&bar[XB_TMO], 1u); break; } }
;     }
;     nloc = mine > 0u ? mine : 1u; nx = cnt > 0u ? cnt : 1u;
; }
.LBB0_117:
	v_writelane_b32 v247, s48, 37
	s_nop 1
	v_writelane_b32 v247, s49, 38
	v_writelane_b32 v247, s50, 39
	v_writelane_b32 v247, s51, 40
	v_writelane_b32 v247, s52, 41
	v_writelane_b32 v247, s53, 42
	v_writelane_b32 v247, s54, 43
	v_writelane_b32 v247, s55, 44
	v_writelane_b32 v247, s56, 45
	v_writelane_b32 v247, s57, 46
	v_writelane_b32 v247, s58, 47
	v_writelane_b32 v247, s59, 48
	v_writelane_b32 v247, s60, 49
	v_writelane_b32 v247, s61, 50
	v_writelane_b32 v247, s62, 51
	v_writelane_b32 v247, s63, 52
	s_or_b64 exec, exec, s[0:1]
	s_add_u32 s6, s98, 0x17d00000
	s_addc_u32 s7, s99, 0
	s_add_u32 s14, s98, 0x23300000
	s_addc_u32 s15, s99, 0
	s_cmpk_lt_i32 s65, 0xb58
	s_cselect_b64 s[0:1], -1, 0
	v_writelane_b32 v247, s0, 53
	s_ashr_i32 s69, s65, 31
	s_ashr_i32 s68, s20, 31
	v_writelane_b32 v247, s1, 54
	s_lshr_b32 s0, s69, 29
	s_add_i32 s0, s65, s0
	s_ashr_i32 s11, s0, 3
	s_and_b32 s0, s0, -8
	s_sub_i32 s10, s65, s0
	s_mul_i32 s0, s10, 11
	s_add_i32 s0, s11, s0
	s_addk_i32 s0, 0xfea0
	s_and_b32 s1, s0, 1
	s_ashr_i32 s5, s0, 1
	s_mul_hi_i32 s0, s65, 0x2e8ba2e9
	s_or_b32 s4, s1, 64
	s_lshr_b32 s1, s0, 31
	s_ashr_i32 s0, s0, 8
	s_add_i32 s0, s0, s1
	s_mul_i32 s1, s0, 0xffffff50
	s_add_i32 s1, s1, s11
	s_lshl_b32 s12, s10, 3
	s_lshl_b32 s0, s0, 2
	s_add_i32 s8, s0, s12
	s_ashr_i32 s0, s1, 31
	s_lshr_b32 s0, s0, 30
	s_add_i32 s0, s1, s0
	s_ashr_i32 s9, s0, 2
	s_and_b32 s0, s0, -4
	s_sub_i32 s0, s1, s0
	s_add_i32 s8, s8, s0
	s_mul_i32 s0, s10, 6
	s_add_i32 s9, s9, s0
	s_mul_hi_i32 s0, s9, 0x2e8ba2e9
	s_lshr_b32 s1, s0, 31
	s_ashr_i32 s0, s0, 3
	s_add_i32 s0, s0, s1
	s_mul_i32 s0, s0, 44
	s_sub_i32 s9, s9, s0
	s_add_u32 s0, s98, 0x80200
	s_addc_u32 s1, s99, 0
	s_add_u32 s92, s98, 0x80400
	s_addc_u32 s93, s99, 0
	s_add_u32 s74, s98, 0x80500
	s_addc_u32 s75, s99, 0
	s_add_u32 s80, s98, 0x80600
	s_addc_u32 s81, s99, 0
	s_add_u32 s82, s98, 0x80700
	v_writelane_b32 v247, s0, 55
	s_addc_u32 s83, s99, 0
	v_lshl_add_u64 v[0:1], v[0:1], 2, s[24:25]
	v_writelane_b32 v247, s1, 56
	s_add_u32 s0, s98, 0x80800
	s_addc_u32 s1, s99, 0
	v_writelane_b32 v247, s0, 57
	v_mov_b32_e32 v189, 0
	v_mov_b32_e32 v218, 0x358637bd
	v_writelane_b32 v247, s1, 58
	s_add_u32 s0, s98, 0x80900
	s_addc_u32 s1, s99, 0
	v_writelane_b32 v247, s0, 59
	v_mov_b32_e32 v219, 1
	v_mov_b64_e32 v[190:191], 0xb58
	v_writelane_b32 v247, s1, 60
	s_add_u32 s0, s98, 0x80a00
	s_addc_u32 s1, s99, 0
	v_writelane_b32 v247, s0, 61
	v_mov_b64_e32 v[192:193], 0xb57
	v_mov_b64_e32 v[194:195], 0x200
	v_writelane_b32 v247, s1, 62
	s_add_u32 s0, s98, 0x80b00
	s_addc_u32 s1, s99, 0
	v_writelane_b32 v247, s0, 63
	v_mov_b64_e32 v[196:197], 0x1ff
	v_mbcnt_hi_u32_b32 v217, -1, v6
	v_writelane_b32 v245, s1, 0
	s_add_u32 s0, s98, 0x80c00
	s_addc_u32 s1, s99, 0
	v_writelane_b32 v245, s0, 1
	v_mov_b64_e32 v[198:199], 0x462
	v_mov_b64_e32 v[200:201], 0x461
	v_writelane_b32 v245, s1, 2
	s_add_u32 s0, s98, 0x80d00
	s_addc_u32 s1, s99, 0
	v_writelane_b32 v245, s0, 3
	v_mov_b32_e32 v220, 0x7800
	s_movk_i32 s33, 0xc00
	v_writelane_b32 v245, s1, 4
	s_add_u32 s0, s98, 0x80e00
	s_addc_u32 s1, s99, 0
	v_writelane_b32 v245, s0, 5
	s_mov_b32 s85, 0
	s_mov_b64 s[86:87], 0x80
	v_writelane_b32 v245, s1, 6
	s_add_u32 s0, s98, 0x80f00
	s_addc_u32 s1, s99, 0
	v_writelane_b32 v245, s0, 7
	s_barrier
	s_nop 0
	v_writelane_b32 v245, s1, 8
	s_add_u32 s0, s98, 0x81000
	s_addc_u32 s1, s99, 0
	v_writelane_b32 v245, s0, 9
	s_nop 1
	v_writelane_b32 v245, s1, 10
	s_add_u32 s0, s98, 0x81100
	s_addc_u32 s1, s99, 0
	v_writelane_b32 v245, s0, 11
	s_nop 1
	v_writelane_b32 v245, s1, 12
	s_add_u32 s0, s98, 0x81200
	s_addc_u32 s1, s99, 0
	v_writelane_b32 v245, s0, 13
	s_nop 1
	v_writelane_b32 v245, s1, 14
	s_add_u32 s0, s98, 0x81300
	s_addc_u32 s1, s99, 0
	v_writelane_b32 v245, s0, 15
	s_cmp_eq_u32 s3, 15
	s_nop 0
	v_writelane_b32 v245, s1, 16
	s_cselect_b64 s[0:1], -1, 0
	v_writelane_b32 v245, s0, 17
	s_cmp_eq_u32 s3, 14
	s_nop 0
	v_writelane_b32 v245, s1, 18
	s_cselect_b64 s[0:1], -1, 0
	v_writelane_b32 v245, s0, 19
	s_cmp_eq_u32 s3, 13
	s_nop 0
	v_writelane_b32 v245, s1, 20
	s_cselect_b64 s[0:1], -1, 0
	v_writelane_b32 v245, s0, 21
	s_cmp_eq_u32 s3, 12
	s_nop 0
	v_writelane_b32 v245, s1, 22
	s_cselect_b64 s[0:1], -1, 0
	v_writelane_b32 v245, s0, 23
	s_cmp_eq_u32 s3, 11
	s_nop 0
	v_writelane_b32 v245, s1, 24
	s_cselect_b64 s[0:1], -1, 0
	v_writelane_b32 v245, s0, 25
	s_cmp_eq_u32 s3, 10
	s_nop 0
	v_writelane_b32 v245, s1, 26
	s_cselect_b64 s[0:1], -1, 0
	v_writelane_b32 v245, s0, 27
	s_cmp_eq_u32 s3, 9
	s_nop 0
	v_writelane_b32 v245, s1, 28
	s_cselect_b64 s[0:1], -1, 0
	v_writelane_b32 v245, s0, 29
	s_cmp_eq_u32 s3, 8
	s_nop 0
	v_writelane_b32 v245, s1, 30
	s_cselect_b64 s[0:1], -1, 0
	v_writelane_b32 v245, s0, 31
	s_cmp_eq_u32 s3, 7
	s_nop 0
	v_writelane_b32 v245, s1, 32
	s_cselect_b64 s[0:1], -1, 0
	v_writelane_b32 v245, s0, 33
	s_cmp_eq_u32 s3, 6
	s_nop 0
	v_writelane_b32 v245, s1, 34
	s_cselect_b64 s[0:1], -1, 0
	v_writelane_b32 v245, s0, 35
	s_cmp_eq_u32 s3, 5
	s_nop 0
	v_writelane_b32 v245, s1, 36
	s_cselect_b64 s[0:1], -1, 0
	v_writelane_b32 v245, s0, 37
	s_cmp_eq_u32 s3, 4
	s_nop 0
	v_writelane_b32 v245, s1, 38
	s_cselect_b64 s[0:1], -1, 0
	v_writelane_b32 v245, s0, 39
	s_cmp_eq_u32 s3, 3
	s_nop 0
	v_writelane_b32 v245, s1, 40
	s_cselect_b64 s[0:1], -1, 0
	v_writelane_b32 v245, s0, 41
	s_cmp_eq_u32 s3, 2
	s_nop 0
	v_writelane_b32 v245, s1, 42
	s_cselect_b64 s[0:1], -1, 0
	v_writelane_b32 v245, s0, 43
	s_cmp_eq_u32 s3, 1
	s_nop 0
	v_writelane_b32 v245, s1, 44
	s_cselect_b64 s[0:1], -1, 0
	v_writelane_b32 v245, s0, 45
	s_cmp_eq_u32 s3, 0
	s_nop 0
	v_writelane_b32 v245, s1, 46
	s_cselect_b64 s[0:1], -1, 0
	v_writelane_b32 v245, s0, 47
;     __device__ __forceinline__ bool next(int i, Unit& u) const {
;         if (i != 0 || c >= 64) return false;
;         u.pm = 64 + (c & 1); u.pn = (c >> 1) & 7; u.kb = (c >> 4) * kslice; return true;
;     }
;     __device__ __forceinline__ void operator()(const f32x4 (&acc)[2][2][4][2], const Unit& u, int wr, int wc, int fr, int fq, const float (&)[8]) const {
;         const int row0 = (u.pm - 64) * BM + wr * 64 + fr, col0 = u.pn * BM + wc * 32 + 8 * fq;
;         float* sp = slab + (size_t)(u.kb / kslice) * (MS * DM);
; __device__ __forceinline__ void mixer_mid(const Params& p, LAS unsigned char* lds, int G, int layer) {
;     ...
;     const int mx_x = (G % 8 == 0) ? (int)(blockIdx.x & 7) : 0, mx_r = (G % 8 == 0) ? (int)(blockIdx.x >> 3) : (int)blockIdx.x, mx_n = (G % 8 == 0) ? G / 8 : G, mx_tot = (G % 8 == 0) ? NCH_X : NCH;
;     u32x4 ra[5], rg[5]; bool preloaded = false;
;     ...
;     for (int ci = mx_r; ci < mx_tot; ci += mx_n) {
	s_nop 1
	v_writelane_b32 v245, s1, 48
	s_add_u32 s0, s98, 0x83400
	s_addc_u32 s1, s99, 0
	v_writelane_b32 v245, s0, 49
	s_nop 1
	v_writelane_b32 v245, s1, 50
	s_add_u32 s0, s98, 0x83500
	s_addc_u32 s1, s99, 0
	v_writelane_b32 v245, s0, 51
	s_nop 1
	v_writelane_b32 v245, s1, 52
	s_add_u32 s0, s98, 0x28500000
	s_addc_u32 s1, s99, 0
	v_writelane_b32 v245, s0, 53
	s_cmpk_lt_i32 s65, 0x200
	s_nop 0
	v_writelane_b32 v245, s1, 54
	s_cselect_b64 s[0:1], -1, 0
	v_writelane_b32 v245, s0, 55
	s_nop 1
	v_writelane_b32 v245, s1, 56
	s_lshr_b32 s0, s69, 24
	s_add_i32 s0, s65, s0
	s_ashr_i32 s0, s0, 8
	s_lshl_b32 s1, s0, 5
	s_sub_i32 s1, s11, s1
	s_lshr_b32 s3, s1, 30
	s_add_i32 s3, s1, s3
	s_and_b32 s13, s3, -4
	s_lshl_b32 s0, s0, 2
	s_sub_i32 s1, s1, s13
	s_add_i32 s0, s0, s12
	s_ashr_i32 s3, s3, 2
	s_add_i32 s26, s0, s1
	s_add_i32 s0, s3, s10
	s_ashr_i32 s1, s0, 31
	s_lshr_b32 s1, s1, 29
	s_add_i32 s1, s0, s1
	s_and_b32 s1, s1, -8
	s_sub_i32 s28, s0, s1
	s_add_u32 s18, s98, 0x27500000
	s_addc_u32 s19, s99, 0
	s_sub_u32 s100, s65, 88
	s_cmp_lt_u32 s100, 64
	s_cselect_b64 s[0:1], -1, 0
	v_writelane_b32 v245, s0, 57
	s_and_b32 s13, s100, 1
	s_or_b32 s22, s13, 64
	v_writelane_b32 v245, s1, 58
	s_ashr_i32 s0, s100, 4
	s_mul_i32 s30, s0, 0xb00
	s_bfe_u32 s3, s100, 0x30001
	s_mul_i32 s1, s22, 0x2c0000
	s_ashr_i32 s31, s30, 31
	s_add_u32 s1, s6, s1
	s_addc_u32 s16, s7, 0
	s_add_u32 s34, s1, s30
	s_addc_u32 s35, s16, s31
	s_add_u32 s16, s34, 0x160000
	v_writelane_b32 v245, s34, 59
	s_addc_u32 s17, s35, 0
	s_ashr_i32 s1, s0, 31
	v_writelane_b32 v245, s35, 60
	v_writelane_b32 v245, s16, 61
	s_lshl_b32 s23, s22, 8
	s_lshl_b32 s2, s3, 8
	v_writelane_b32 v245, s17, 62
	s_lshl_b64 s[16:17], s[0:1], 22
	s_add_u32 s16, s18, s16
	v_writelane_b32 v244, s18, 0
	s_addc_u32 s17, s19, s17
	s_add_i32 s1, s23, 0xffffc000
	v_writelane_b32 v244, s19, 1
	v_writelane_b32 v244, s16, 2
	s_cmpk_lt_i32 s65, 0x462
	v_writelane_b32 v245, s2, 63
	v_writelane_b32 v244, s17, 3
	s_mov_b64 s[16:17], 0x1400
	v_lshl_add_u64 v[184:185], v[0:1], 0, s[16:17]
	s_mov_b64 s[16:17], 0x2400
	v_lshl_add_u64 v[186:187], v[0:1], 0, s[16:17]
	v_writelane_b32 v244, s1, 4
	s_cselect_b64 s[16:17], -1, 0
	s_mul_hi_i32 s1, s65, 0x78787879
	v_writelane_b32 v244, s16, 5
	s_lshr_b32 s23, s65, 3
	s_ashr_i32 s24, s20, 3
	v_writelane_b32 v244, s17, 6
	s_lshr_b32 s16, s1, 31
	s_ashr_i32 s1, s1, 8
	s_add_i32 s1, s1, s16
	s_min_i32 s16, s10, 2
	s_mul_i32 s17, s1, 0xffffffbc
	s_add_i32 s16, s16, s11
	s_add_i32 s11, s17, s11
	s_lshl_b32 s1, s1, 2
	s_add_i32 s1, s1, s12
	s_ashr_i32 s12, s11, 31
	s_lshr_b32 s12, s12, 30
	s_add_i32 s12, s11, s12
	s_and_b32 s17, s12, -4
	s_sub_i32 s11, s11, s17
	s_add_i32 s11, s1, s11
	s_ashr_i32 s1, s12, 2
	s_mul_i32 s12, s10, 3
	s_add_i32 s1, s1, s12
	s_mul_hi_i32 s12, s1, 0x78787879
	s_lshr_b32 s17, s12, 31
	s_ashr_i32 s12, s12, 3
	s_add_i32 s12, s12, s17
	s_mul_i32 s12, s12, 17
	s_sub_i32 s12, s1, s12
	s_lshl_b32 s1, s10, 2
	s_add_i32 s1, s1, s16
	s_addk_i32 s1, 0xff78
	s_and_b32 s10, s16, 1
	s_or_b32 s10, s10, 64
	s_ashr_i32 s16, s1, 1
	s_and_b32 s1, s20, 7
	s_and_b32 s17, s65, 7
	s_cmp_eq_u32 s1, 0
	s_mulk_i32 s17, 0x84
	s_cselect_b32 s1, s17, 0
	v_writelane_b32 v244, s1, 7
	s_movk_i32 s1, 0x420
	s_cselect_b32 s17, s24, s20
	s_cselect_b32 s2, s23, s65
	s_cselect_b32 s1, 0x84, s1
	v_writelane_b32 v244, s17, 8
	v_writelane_b32 v244, s2, 9
	s_cmp_lt_i32 s2, s1
	v_writelane_b32 v244, s1, 10
	s_cselect_b64 s[18:19], -1, 0
	v_writelane_b32 v244, s18, 11
	s_lshl_b32 s17, s0, 10
	s_lshl_b32 s0, s22, 20
	v_writelane_b32 v244, s19, 12
	s_ashr_i32 s18, s17, 31
	s_lshl_b32 s1, s3, 20
	s_add_u32 s0, s14, s0
	v_writelane_b32 v244, s1, 13
	s_addc_u32 s1, s15, 0
	s_add_u32 s0, s0, s17
	s_addc_u32 s1, s1, s18
	s_add_u32 s22, s0, 0x80000
	v_writelane_b32 v244, s0, 14
	s_addc_u32 s23, s1, 0
	s_cmpk_lt_i32 s65, 0xb00
	v_writelane_b32 v244, s1, 15
	v_writelane_b32 v244, s22, 16
	s_cselect_b32 s4, s8, s4
	s_mul_i32 s2, s28, 0x2c0000
	v_writelane_b32 v244, s23, 17
	s_cselect_b32 s22, s9, s5
	s_ashr_i32 s5, s4, 31
	s_lshl_b64 s[0:1], s[4:5], 20
	s_add_u32 s8, s72, s0
	s_mov_b32 s0, s22
	s_addc_u32 s9, s73, s1
	s_ashr_i32 s23, s22, 31
	v_writelane_b32 v244, s0, 18
	s_nop 1
	v_writelane_b32 v244, s1, 19
; #define LAS __attribute__((address_space(3)))
; template <class Epi, class Sched, bool ALIGN_EPI = false, bool SP2 = false>
; __device__ __forceinline__ void gemm_phase(LAS unsigned char* lds, const Gemm g, const Sched& S, const Epi& E) {
;     int tid = threadIdx.x; asm volatile("" : "+v"(tid));
;     const int wid = __builtin_amdgcn_readfirstlane(tid >> 6), lane = tid & 63, wr = wid >> 2, wc = wid & 3, fr = lane & 15, fq = lane >> 4;
;     const int K = g.K, nt = g.nt;
;     unsigned voffA[2], voffB[2];
; #pragma unroll
;     for (int i = 0; i < 2; ++i) { int R, C; stage_rc(tid * 16 + i * 8192, R, C); const int Rb = Epi::PERM ? ((R & ~31) + perm32(R & 31)) : R;
;         voffA[i] = (unsigned)(R * K + C) * 2u; voffB[i] = (unsigned)(Rb * K + C) * 2u; }
;     const size_t kstep = (size_t)(BK * 2);
;     const size_t hstep = (size_t)HALF * K * 2;
;     const size_t tstep = 2 * hstep;
;     const unsigned ldsw = (unsigned)wid * 1024u;
;     const int aoff = lds_byte(wr * 64 + fr, fq * 8), boff = lds_byte(wc * 32 + fr, fq * 8);
;     ...
;     Unit cur, nxt; int ui = 0;
;     if (!S.next(0, cur)) return;
;     f32x4 acc[2][2][4][2];
; #pragma unroll
;     for (int a = 0; a < 2; ++a)
; #pragma unroll
;         for (int b = 0; b < 2; ++b)
; #pragma unroll
;             for (int m = 0; m < 4; ++m)
; #pragma unroll
;                 for (int n = 0; n < 2; ++n) acc[a][b][m][n] = (f32x4){0.f, 0.f, 0.f, 0.f};
;     bf16x8 At[4][2], B0[2][2], B1[2][2];
;     const char* cA = (const char*)g.A + (size_t)cur.pm * tstep + cur.kb; const char* cB = (const char*)g.Bt + (size_t)cur.pn * tstep + cur.kb;
;     S.a_ready(cur);
;     float sv[8];
	s_lshl_b64 s[0:1], s[22:23], 20
	v_writelane_b32 v244, s0, 20
	s_nop 1
	v_writelane_b32 v244, s1, 21
	s_mov_b32 s0, s4
	v_writelane_b32 v244, s0, 22
	s_nop 1
	v_writelane_b32 v244, s1, 23
	s_lshl_b64 s[0:1], s[4:5], 10
	v_writelane_b32 v244, s0, 24
	s_nop 1
	v_writelane_b32 v244, s1, 25
	s_add_u32 s0, s8, 0x80000
	v_writelane_b32 v244, s8, 26
	s_addc_u32 s1, s9, 0
	s_ashr_i32 s27, s26, 31
	v_writelane_b32 v244, s9, 27
	v_writelane_b32 v244, s0, 28
	s_nop 1
	v_writelane_b32 v244, s1, 29
	s_mul_i32 s1, s26, 0x2c0000
	v_writelane_b32 v244, s2, 30
	s_ashr_i32 s2, s2, 31
	s_mul_hi_i32 s0, s26, 0x2c0000
	s_add_u32 s4, s6, s1
	s_addc_u32 s5, s7, s0
	v_writelane_b32 v244, s2, 31
	s_add_u32 s0, s4, 0x160000
	v_writelane_b32 v244, s4, 32
	s_addc_u32 s1, s5, 0
	s_cmpk_lt_i32 s65, 0x440
	v_writelane_b32 v244, s5, 33
	s_cselect_b32 s8, s11, s10
	v_writelane_b32 v244, s0, 34
	s_cselect_b32 s4, s12, s16
	s_ashr_i32 s9, s8, 31
	v_writelane_b32 v244, s1, 35
	s_lshl_b64 s[0:1], s[8:9], 20
	s_add_u32 s10, s72, s0
	s_mov_b32 s0, s4
	s_addc_u32 s11, s73, s1
	s_ashr_i32 s5, s4, 31
	v_writelane_b32 v244, s0, 36
	s_mov_b32 s2, s28
	s_nop 0
	v_writelane_b32 v244, s1, 37
	s_lshl_b64 s[0:1], s[4:5], 20
	v_writelane_b32 v244, s0, 38
	s_nop 1
	v_writelane_b32 v244, s1, 39
	s_mov_b32 s0, s8
	v_writelane_b32 v244, s0, 40
	s_nop 1
	v_writelane_b32 v244, s1, 41
	s_lshl_b64 s[0:1], s[8:9], 10
	v_writelane_b32 v244, s0, 42
	s_nop 1
	v_writelane_b32 v244, s1, 43
	s_add_u32 s0, s10, 0x80000
	v_writelane_b32 v244, s10, 44
	s_addc_u32 s1, s11, 0
	s_ashr_i32 s29, s28, 31
	v_writelane_b32 v244, s11, 45
	v_writelane_b32 v244, s0, 46
	s_lshl_b64 s[4:5], s[28:29], 20
	s_nop 0
	v_writelane_b32 v244, s1, 47
	s_mov_b32 s0, s26
	v_writelane_b32 v244, s0, 48
	s_nop 1
	v_writelane_b32 v244, s1, 49
	v_writelane_b32 v244, s2, 50
	s_lshl_b64 s[0:1], s[26:27], 20
	s_nop 0
	v_writelane_b32 v244, s3, 51
	v_writelane_b32 v244, s4, 52
	s_mov_b32 s2, 0x16000
	s_nop 0
	v_writelane_b32 v244, s5, 53
	s_add_u32 s4, s14, s0
	s_mul_i32 s0, s21, s20
	s_mul_i32 s0, s0, s64
	s_addc_u32 s5, s15, s1
	v_writelane_b32 v244, s0, 54
	s_add_u32 s0, s4, 0x80000
	v_writelane_b32 v244, s4, 55
	s_addc_u32 s1, s5, 0
	s_nop 0
	v_writelane_b32 v244, s5, 56
	v_writelane_b32 v244, s0, 57
	s_nop 1
	v_writelane_b32 v244, s1, 58
	s_mul_i32 s0, s13, 0x2c0000
	s_add_u32 s0, s0, s30
	s_addc_u32 s1, 0, s31
	s_add_u32 s0, s98, s0
	s_addc_u32 s1, s99, s1
	v_writelane_b32 v244, s30, 59
	s_add_u32 s0, s0, 0x22e60080
	v_writelane_b32 v244, s31, 60
	s_addc_u32 s1, s1, 0
	v_writelane_b32 v244, s0, 61
	s_ashr_i32 s67, s66, 31
	s_lshl_b64 s[4:5], s[66:67], 13
	v_writelane_b32 v244, s1, 62
	v_readlane_b32 s1, v247, 36
	s_addk_i32 s1, 0x4000
	s_lshl_b32 s0, s13, 20
	v_writelane_b32 v244, s1, 63
	s_lshl_b32 s1, s65, 4
	v_writelane_b32 v246, s1, 0
	s_lshl_b32 s1, s20, 4
	v_writelane_b32 v246, s1, 1
	v_writelane_b32 v246, s4, 2
	s_nop 1
	v_writelane_b32 v246, s5, 3
	s_lshl_b64 s[4:5], s[66:67], 2
	v_writelane_b32 v246, s4, 4
	s_nop 1
	v_writelane_b32 v246, s5, 5
	s_lshl_b64 s[4:5], s[66:67], 12
	s_add_u32 s0, s0, s17
	s_addc_u32 s1, 0, s18
	v_writelane_b32 v246, s4, 6
	s_add_u32 s0, s98, s0
	s_addc_u32 s1, s99, s1
	v_writelane_b32 v246, s5, 7
	v_writelane_b32 v246, s17, 8
	s_add_u32 s0, s0, 0x27380080
	v_writelane_b32 v246, s18, 9
	s_addc_u32 s1, s1, 0
	v_writelane_b32 v246, s0, 10
	s_movk_i32 s18, 0x2200
	s_nop 0
	v_writelane_b32 v246, s1, 11
	s_mul_i32 s0, s3, 0x2c0000
	v_writelane_b32 v246, s0, 12
	s_add_i32 s0, 0, 0x20000
	v_writelane_b32 v246, s0, 13
	s_add_i32 s0, 0, 0x22000
	v_writelane_b32 v246, s0, 14
	s_add_i32 s0, 0, 0x22004
	v_writelane_b32 v246, s0, 15
	s_add_i32 s0, 0, 0x11400
	v_writelane_b32 v246, s0, 16
	s_add_i32 s0, 0, 0x7000
	v_writelane_b32 v246, s0, 17
	s_mov_b32 s1, 0
	s_mov_b32 s0, s20
	v_writelane_b32 v246, s0, 18
	s_mov_b32 s3, 0x2aaaaaab
	s_nop 0
	v_writelane_b32 v246, s1, 19
	v_writelane_b32 v246, s66, 20
	s_nop 1
	v_writelane_b32 v246, s67, 21
	v_writelane_b32 v246, s65, 22
	v_writelane_b32 v246, s74, 23
	s_nop 1
	v_writelane_b32 v246, s75, 24
	v_writelane_b32 v246, s80, 25
	s_nop 1
	v_writelane_b32 v246, s81, 26
	v_writelane_b32 v246, s82, 27
	s_nop 1
	v_writelane_b32 v246, s83, 28
	s_branch .LBB0_119

; #define LAS __attribute__((address_space(3)))
; __device__ __forceinline__ unsigned cvt_pk_bf16(float lo, float hi) { unsigned r; asm volatile("v_cvt_pk_bf16_f32 %0, %1, %2" : "=v"(r) : "v"(lo), "v"(hi)); return r; }
;     __device__ __forceinline__ void operator()(const f32x4 (&acc)[2][2][4][2], const Unit& u, int wr, int wc, int fr, int fq, const float (&sv)[8]) const {
;         const int row0 = u.pm * BM + wr * 64 + fr, col0 = u.pn * HALF + wc * 32 + 8 * fq;
; #pragma unroll
;         for (int ai = 0; ai < 2; ++ai)
; #pragma unroll
;             for (int m = 0; m < 4; ++m) {
;                 const int row = row0 + ai * HALF + m * 16;
;                 const float rinv = __builtin_amdgcn_rsqf(sv[ai * 4 + m] * (1.f / DM) + EPS), rneg = rinv * -1.44269504f, r2 = rinv * rinv;
;                 const f32x4 g0 = acc[ai][0][m][0], g1 = acc[ai][0][m][1], u0 = acc[ai][1][m][0], u1 = acc[ai][1][m][1];
;                 f32x4 e0, e1;
; #pragma unroll
;                 for (int j = 0; j < 4; ++j) { e0[j] = __builtin_amdgcn_rcpf(1.f + __builtin_amdgcn_exp2f(g0[j] * rneg)); e1[j] = __builtin_amdgcn_rcpf(1.f + __builtin_amdgcn_exp2f(g1[j] * rneg)); }
;                 const f32x4 a0 = (g0 * u0) * (e0 * r2), a1 = (g1 * u1) * (e1 * r2);
;                 u32x4 w;
;                 w.x = cvt_pk_bf16(a0[0], a0[1]); w.y = cvt_pk_bf16(a0[2], a0[3]); w.z = cvt_pk_bf16(a1[0], a1[1]); w.w = cvt_pk_bf16(a1[2], a1[3]);
;                 *(u32x4*)(O + (size_t)row * DFF + col0) = w;
;             }
;     }
; template <class Epi, class Sched, bool ALIGN_EPI = false, bool SP2 = false>
; __device__ __forceinline__ void gemm_phase(LAS unsigned char* lds, const Gemm g, const Sched& S, const Epi& E) {
;     ...
;                 for (int m = 0; m < 4; ++m) sv[ai * 4 + m] = *(const LAS float*)(lds + STAGE_BYTES + (ui & 1) * 1024 + 4 * (ai * HALF + wr * 64 + m * 16 + fr));
.LBB0_137:
	s_lshl_b32 s13, s51, 10
	s_and_b32 s13, s13, 0x400
	v_add_u32_e32 v140, s13, v149
	ds_read2_b32 v[152:153], v140 offset1:16
	v_pk_mul_f32 v[118:119], v[126:127], v[118:119]
	v_pk_mul_f32 v[116:117], v[124:125], v[116:117]
	v_pk_mul_f32 v[114:115], v[122:123], v[114:115]
	v_pk_mul_f32 v[112:113], v[120:121], v[112:113]
	s_waitcnt lgkmcnt(0)
	v_fmamk_f32 v141, v152, 0x3a000000, v218
	v_rsq_f32_e32 v152, v141
	ds_read2_b32 v[144:145], v140 offset0:32 offset1:48
	ds_read2_b32 v[142:143], v140 offset0:128 offset1:144
	v_lshl_or_b32 v154, s49, 7, v148
	v_lshl_add_u32 v151, s50, 8, v146
	v_mul_f32_e32 v161, 0xbfb8aa3b, v152
	v_mul_f32_e32 v141, v124, v161
	v_mul_f32_e32 v156, v120, v161
	v_exp_f32_e32 v157, v141
	v_exp_f32_e32 v156, v156
	v_mul_f32_e32 v158, v125, v161
	v_mul_f32_e32 v162, v122, v161
	v_add_f32_e32 v157, 1.0, v157
	v_add_f32_e32 v159, 1.0, v156
	v_rcp_f32_e32 v156, v157
	v_exp_f32_e32 v157, v158
	v_mul_f32_e32 v158, v121, v161
	v_exp_f32_e32 v160, v158
	v_rcp_f32_e32 v158, v159
	v_mul_f32_e32 v163, v127, v161
	v_exp_f32_e32 v162, v162
	v_add_f32_e32 v159, 1.0, v160
	v_mul_f32_e32 v160, v126, v161
	v_mul_f32_e32 v161, v123, v161
	v_exp_f32_e32 v160, v160
	v_exp_f32_e32 v163, v163
	v_exp_f32_e32 v164, v161
	v_add_f32_e32 v157, 1.0, v157
	v_add_f32_e32 v160, 1.0, v160
	v_add_f32_e32 v162, 1.0, v162
	v_add_f32_e32 v161, 1.0, v163
	v_add_f32_e32 v163, 1.0, v164
	v_rcp_f32_e32 v157, v157
	v_rcp_f32_e32 v160, v160
	v_rcp_f32_e32 v162, v162
	v_rcp_f32_e32 v161, v161
	v_rcp_f32_e32 v163, v163
	v_rcp_f32_e32 v159, v159
	v_mul_f32_e32 v152, v152, v152
	v_pk_mul_f32 v[124:125], v[152:153], v[156:157] op_sel_hi:[0,1]
	v_pk_mul_f32 v[126:127], v[152:153], v[160:161] op_sel_hi:[0,1]
	v_pk_mul_f32 v[122:123], v[152:153], v[162:163] op_sel_hi:[0,1]
	v_pk_mul_f32 v[118:119], v[118:119], v[126:127]
	v_pk_mul_f32 v[116:117], v[116:117], v[124:125]
	v_pk_mul_f32 v[120:121], v[152:153], v[158:159] op_sel_hi:[0,1]
	v_pk_mul_f32 v[114:115], v[114:115], v[122:123]
	ds_read2_b32 v[140:141], v140 offset0:160 offset1:176
	v_pk_mul_f32 v[112:113], v[112:113], v[120:121]
	v_cvt_pk_bf16_f32 v116, v116, v117
	v_cvt_pk_bf16_f32 v117, v118, v119
	v_ashrrev_i32_e32 v155, 31, v154
	v_cvt_pk_bf16_f32 v118, v112, v113
	v_cvt_pk_bf16_f32 v119, v114, v115
	v_fmamk_f32 v114, v153, 0x3a000000, v218
	v_rsq_f32_e32 v124, v114
	v_mov_b64_e32 v[112:113], s[6:7]
	s_movk_i32 s13, 0x2c00
	v_mad_i64_i32 v[120:121], s[24:25], v151, s13, v[112:113]
	v_lshlrev_b64 v[114:115], 1, v[154:155]
	v_lshl_add_u64 v[120:121], v[120:121], 0, v[114:115]
	v_mul_f32_e32 v122, 0xbfb8aa3b, v124
	v_mul_f32_e32 v125, v104, v122
	global_store_dwordx4 v[120:121], v[116:119], off
	v_mul_f32_e32 v123, v108, v122
	v_exp_f32_e32 v125, v125
	v_mul_f32_e32 v118, v109, v122
	v_exp_f32_e32 v119, v118
	v_mul_f32_e32 v118, v105, v122
	v_exp_f32_e32 v123, v123
	v_exp_f32_e32 v120, v118
	v_add_f32_e32 v117, 1.0, v125
	v_mul_f32_e32 v121, v106, v122
	v_add_f32_e32 v116, 1.0, v123
	v_rcp_f32_e32 v118, v117
	v_add_f32_e32 v117, 1.0, v119
	v_add_f32_e32 v119, 1.0, v120
	v_mul_f32_e32 v120, v110, v122
	v_exp_f32_e32 v121, v121
	v_mul_f32_e32 v123, v111, v122
	v_mul_f32_e32 v122, v107, v122
	v_exp_f32_e32 v123, v123
	v_exp_f32_e32 v125, v122
	v_add_f32_e32 v121, 1.0, v121
	v_rcp_f32_e32 v116, v116
	v_rcp_f32_e32 v117, v117
	v_exp_f32_e32 v120, v120
	v_rcp_f32_e32 v122, v121
	v_add_f32_e32 v121, 1.0, v123
	v_add_f32_e32 v123, 1.0, v125
	v_rcp_f32_e32 v119, v119
	v_rcp_f32_e32 v123, v123
	v_or_b32_e32 v125, 16, v151
	v_mul_f32_e32 v124, v124, v124
	v_add_f32_e32 v120, 1.0, v120
	v_pk_mul_f32 v[100:101], v[108:109], v[100:101]
	v_pk_mul_f32 v[108:109], v[124:125], v[116:117] op_sel_hi:[0,1]
	v_rcp_f32_e32 v120, v120
	v_rcp_f32_e32 v121, v121
	v_pk_mul_f32 v[100:101], v[100:101], v[108:109]
	v_pk_mul_f32 v[98:99], v[106:107], v[98:99]
	v_pk_mul_f32 v[96:97], v[104:105], v[96:97]
	v_pk_mul_f32 v[104:105], v[124:125], v[118:119] op_sel_hi:[0,1]
	v_pk_mul_f32 v[106:107], v[124:125], v[122:123] op_sel_hi:[0,1]
	v_pk_mul_f32 v[106:107], v[98:99], v[106:107]
	v_pk_mul_f32 v[98:99], v[96:97], v[104:105]
	v_cvt_pk_bf16_f32 v96, v100, v101
	s_waitcnt lgkmcnt(0)
	v_fmamk_f32 v100, v144, 0x3a000000, v218
	v_rsq_f32_e32 v104, v100
	v_pk_mul_f32 v[102:103], v[110:111], v[102:103]
	v_pk_mul_f32 v[110:111], v[124:125], v[120:121] op_sel_hi:[0,1]
	v_pk_mul_f32 v[102:103], v[102:103], v[110:111]
	v_mad_i64_i32 v[100:101], s[24:25], v125, s13, v[112:113]
	v_cvt_pk_bf16_f32 v97, v102, v103
	v_cvt_pk_bf16_f32 v98, v98, v99
	v_lshl_add_u64 v[100:101], v[100:101], 0, v[114:115]
	v_mul_f32_e32 v102, 0xbfb8aa3b, v104
	v_cvt_pk_bf16_f32 v99, v106, v107
	v_mul_f32_e32 v105, v88, v102
	global_store_dwordx4 v[100:101], v[96:99], off
	v_mul_f32_e32 v103, v92, v102
	v_exp_f32_e32 v105, v105
	v_mul_f32_e32 v98, v93, v102
	v_exp_f32_e32 v99, v98
	v_mul_f32_e32 v98, v89, v102
	v_exp_f32_e32 v103, v103
	v_exp_f32_e32 v100, v98
	v_add_f32_e32 v97, 1.0, v105
	v_mul_f32_e32 v101, v90, v102
	v_add_f32_e32 v96, 1.0, v103
	v_rcp_f32_e32 v98, v97
	v_add_f32_e32 v97, 1.0, v99
	v_add_f32_e32 v99, 1.0, v100
	v_mul_f32_e32 v100, v94, v102
	v_exp_f32_e32 v101, v101
	v_mul_f32_e32 v103, v95, v102
	v_mul_f32_e32 v102, v91, v102
	v_exp_f32_e32 v103, v103
	v_exp_f32_e32 v105, v102
	v_add_f32_e32 v101, 1.0, v101
	v_rcp_f32_e32 v96, v96
	v_rcp_f32_e32 v97, v97
	v_exp_f32_e32 v100, v100
	v_rcp_f32_e32 v102, v101
	v_add_f32_e32 v101, 1.0, v103
	v_add_f32_e32 v103, 1.0, v105
	v_rcp_f32_e32 v99, v99
	v_rcp_f32_e32 v103, v103
	v_or_b32_e32 v105, 32, v151
	v_mul_f32_e32 v104, v104, v104
	v_add_f32_e32 v100, 1.0, v100
	v_pk_mul_f32 v[84:85], v[92:93], v[84:85]
; __device__ __forceinline__ unsigned cvt_pk_bf16(float lo, float hi) { unsigned r; asm volatile("v_cvt_pk_bf16_f32 %0, %1, %2" : "=v"(r) : "v"(lo), "v"(hi)); return r; }
;     __device__ __forceinline__ void operator()(const f32x4 (&acc)[2][2][4][2], const Unit& u, int wr, int wc, int fr, int fq, const float (&sv)[8]) const {
;     ...
;             for (int m = 0; m < 4; ++m) {
;                 const int row = row0 + ai * HALF + m * 16;
;                 const float rinv = __builtin_amdgcn_rsqf(sv[ai * 4 + m] * (1.f / DM) + EPS), rneg = rinv * -1.44269504f, r2 = rinv * rinv;
;                 const f32x4 g0 = acc[ai][0][m][0], g1 = acc[ai][0][m][1], u0 = acc[ai][1][m][0], u1 = acc[ai][1][m][1];
;                 f32x4 e0, e1;
; #pragma unroll
;                 for (int j = 0; j < 4; ++j) { e0[j] = __builtin_amdgcn_rcpf(1.f + __builtin_amdgcn_exp2f(g0[j] * rneg)); e1[j] = __builtin_amdgcn_rcpf(1.f + __builtin_amdgcn_exp2f(g1[j] * rneg)); }
;                 const f32x4 a0 = (g0 * u0) * (e0 * r2), a1 = (g1 * u1) * (e1 * r2);
;                 u32x4 w;
;                 w.x = cvt_pk_bf16(a0[0], a0[1]); w.y = cvt_pk_bf16(a0[2], a0[3]); w.z = cvt_pk_bf16(a1[0], a1[1]); w.w = cvt_pk_bf16(a1[2], a1[3]);
;                 *(u32x4*)(O + (size_t)row * DFF + col0) = w;
;             }
	v_pk_mul_f32 v[92:93], v[104:105], v[96:97] op_sel_hi:[0,1]
	v_rcp_f32_e32 v100, v100
	v_rcp_f32_e32 v101, v101
	v_pk_mul_f32 v[84:85], v[84:85], v[92:93]
	v_pk_mul_f32 v[82:83], v[90:91], v[82:83]
	v_pk_mul_f32 v[80:81], v[88:89], v[80:81]
	v_pk_mul_f32 v[88:89], v[104:105], v[98:99] op_sel_hi:[0,1]
	v_pk_mul_f32 v[90:91], v[104:105], v[102:103] op_sel_hi:[0,1]
	v_pk_mul_f32 v[90:91], v[82:83], v[90:91]
	v_pk_mul_f32 v[82:83], v[80:81], v[88:89]
	v_cvt_pk_bf16_f32 v80, v84, v85
	v_fmamk_f32 v84, v145, 0x3a000000, v218
	v_rsq_f32_e32 v88, v84
	v_pk_mul_f32 v[86:87], v[94:95], v[86:87]
	v_pk_mul_f32 v[94:95], v[104:105], v[100:101] op_sel_hi:[0,1]
	v_pk_mul_f32 v[86:87], v[86:87], v[94:95]
	v_mad_i64_i32 v[84:85], s[24:25], v105, s13, v[112:113]
	v_cvt_pk_bf16_f32 v81, v86, v87
	v_cvt_pk_bf16_f32 v82, v82, v83
	v_lshl_add_u64 v[84:85], v[84:85], 0, v[114:115]
	v_mul_f32_e32 v86, 0xbfb8aa3b, v88
	v_cvt_pk_bf16_f32 v83, v90, v91
	v_mul_f32_e32 v89, v72, v86
	global_store_dwordx4 v[84:85], v[80:83], off
	v_mul_f32_e32 v87, v76, v86
	v_exp_f32_e32 v89, v89
	v_mul_f32_e32 v82, v77, v86
	v_exp_f32_e32 v83, v82
	v_mul_f32_e32 v82, v73, v86
	v_exp_f32_e32 v87, v87
	v_exp_f32_e32 v84, v82
	v_add_f32_e32 v81, 1.0, v89
	v_mul_f32_e32 v85, v74, v86
	v_add_f32_e32 v80, 1.0, v87
	v_rcp_f32_e32 v82, v81
	v_add_f32_e32 v81, 1.0, v83
	v_add_f32_e32 v83, 1.0, v84
	v_mul_f32_e32 v84, v78, v86
	v_exp_f32_e32 v85, v85
	v_mul_f32_e32 v87, v79, v86
	v_mul_f32_e32 v86, v75, v86
	v_exp_f32_e32 v87, v87
	v_exp_f32_e32 v89, v86
	v_add_f32_e32 v85, 1.0, v85
	v_rcp_f32_e32 v80, v80
	v_rcp_f32_e32 v81, v81
	v_rcp_f32_e32 v86, v85
	v_add_f32_e32 v85, 1.0, v87
	v_add_f32_e32 v87, 1.0, v89
	v_exp_f32_e32 v84, v84
	v_rcp_f32_e32 v83, v83
	v_rcp_f32_e32 v87, v87
	v_or_b32_e32 v89, 48, v151
	v_mul_f32_e32 v88, v88, v88
	v_pk_mul_f32 v[68:69], v[76:77], v[68:69]
	v_pk_mul_f32 v[76:77], v[88:89], v[80:81] op_sel_hi:[0,1]
	v_add_f32_e32 v84, 1.0, v84
	v_pk_mul_f32 v[68:69], v[68:69], v[76:77]
	v_pk_mul_f32 v[66:67], v[74:75], v[66:67]
	v_pk_mul_f32 v[64:65], v[72:73], v[64:65]
	v_pk_mul_f32 v[72:73], v[88:89], v[82:83] op_sel_hi:[0,1]
	v_pk_mul_f32 v[74:75], v[88:89], v[86:87] op_sel_hi:[0,1]
	v_rcp_f32_e32 v84, v84
	v_rcp_f32_e32 v85, v85
	v_pk_mul_f32 v[74:75], v[66:67], v[74:75]
	v_pk_mul_f32 v[66:67], v[64:65], v[72:73]
	v_cvt_pk_bf16_f32 v64, v68, v69
	v_fmamk_f32 v68, v142, 0x3a000000, v218
	v_rsq_f32_e32 v72, v68
	v_mad_i64_i32 v[68:69], s[24:25], v89, s13, v[112:113]
	v_pk_mul_f32 v[70:71], v[78:79], v[70:71]
	v_pk_mul_f32 v[78:79], v[88:89], v[84:85] op_sel_hi:[0,1]
	v_lshl_add_u64 v[68:69], v[68:69], 0, v[114:115]
	v_pk_mul_f32 v[70:71], v[70:71], v[78:79]
	v_add_u32_e32 v73, 0x80, v151
	v_cvt_pk_bf16_f32 v65, v70, v71
	v_cvt_pk_bf16_f32 v66, v66, v67
	v_cvt_pk_bf16_f32 v67, v74, v75
	global_store_dwordx4 v[68:69], v[64:67], off
	v_mul_f32_e32 v69, 0xbfb8aa3b, v72
	v_mul_f32_e32 v70, v50, v69
	v_mul_f32_e32 v65, v48, v69
	v_mul_f32_e32 v66, v53, v69
	v_exp_f32_e32 v65, v65
	v_exp_f32_e32 v67, v66
	v_mul_f32_e32 v66, v49, v69
	v_exp_f32_e32 v68, v66
	v_mul_f32_e32 v64, v52, v69
	v_add_f32_e32 v65, 1.0, v65
	v_exp_f32_e32 v64, v64
	v_rcp_f32_e32 v66, v65
	v_add_f32_e32 v65, 1.0, v67
	v_add_f32_e32 v67, 1.0, v68
	v_mul_f32_e32 v68, v54, v69
	v_mul_f32_e32 v71, v55, v69
	v_mul_f32_e32 v69, v51, v69
	v_exp_f32_e32 v70, v70
	v_exp_f32_e32 v71, v71
	v_exp_f32_e32 v74, v69
	v_add_f32_e32 v64, 1.0, v64
	v_rcp_f32_e32 v64, v64
	v_rcp_f32_e32 v65, v65
	v_exp_f32_e32 v68, v68
	v_add_f32_e32 v70, 1.0, v70
	v_add_f32_e32 v69, 1.0, v71
	v_add_f32_e32 v71, 1.0, v74
	v_rcp_f32_e32 v67, v67
	v_rcp_f32_e32 v70, v70
	v_rcp_f32_e32 v71, v71
	v_mul_f32_e32 v72, v72, v72
	v_add_f32_e32 v68, 1.0, v68
	v_pk_mul_f32 v[52:53], v[52:53], v[60:61]
	v_pk_mul_f32 v[60:61], v[72:73], v[64:65] op_sel_hi:[0,1]
	v_rcp_f32_e32 v68, v68
	v_rcp_f32_e32 v69, v69
	v_pk_mul_f32 v[52:53], v[52:53], v[60:61]
	v_pk_mul_f32 v[50:51], v[50:51], v[58:59]
	v_pk_mul_f32 v[48:49], v[48:49], v[56:57]
	v_pk_mul_f32 v[56:57], v[72:73], v[66:67] op_sel_hi:[0,1]
	v_pk_mul_f32 v[58:59], v[72:73], v[70:71] op_sel_hi:[0,1]
	v_pk_mul_f32 v[58:59], v[50:51], v[58:59]
	v_pk_mul_f32 v[50:51], v[48:49], v[56:57]
	v_cvt_pk_bf16_f32 v48, v52, v53
	v_fmamk_f32 v52, v143, 0x3a000000, v218
	v_rsq_f32_e32 v56, v52
	v_pk_mul_f32 v[54:55], v[54:55], v[62:63]
	v_pk_mul_f32 v[62:63], v[72:73], v[68:69] op_sel_hi:[0,1]
	v_pk_mul_f32 v[54:55], v[54:55], v[62:63]
	v_mad_i64_i32 v[52:53], s[24:25], v73, s13, v[112:113]
	v_cvt_pk_bf16_f32 v49, v54, v55
	v_cvt_pk_bf16_f32 v50, v50, v51
	v_lshl_add_u64 v[52:53], v[52:53], 0, v[114:115]
	v_mul_f32_e32 v54, 0xbfb8aa3b, v56
	v_cvt_pk_bf16_f32 v51, v58, v59
	v_mul_f32_e32 v57, v24, v54
	global_store_dwordx4 v[52:53], v[48:51], off
	v_mul_f32_e32 v55, v36, v54
	v_exp_f32_e32 v57, v57
	v_mul_f32_e32 v50, v37, v54
	v_exp_f32_e32 v51, v50
	v_mul_f32_e32 v50, v25, v54
	v_exp_f32_e32 v55, v55
	v_exp_f32_e32 v52, v50
	v_add_f32_e32 v49, 1.0, v57
	v_mul_f32_e32 v53, v26, v54
	v_add_f32_e32 v48, 1.0, v55
	v_rcp_f32_e32 v50, v49
	v_add_f32_e32 v49, 1.0, v51
	v_add_f32_e32 v51, 1.0, v52
	v_mul_f32_e32 v52, v38, v54
	v_exp_f32_e32 v53, v53
	v_mul_f32_e32 v55, v39, v54
	v_mul_f32_e32 v54, v27, v54
	v_exp_f32_e32 v55, v55
	v_exp_f32_e32 v57, v54
	v_add_f32_e32 v53, 1.0, v53
	v_rcp_f32_e32 v48, v48
	v_rcp_f32_e32 v49, v49
	v_exp_f32_e32 v52, v52
	v_rcp_f32_e32 v54, v53
	v_add_f32_e32 v53, 1.0, v55
	v_add_f32_e32 v55, 1.0, v57
	v_rcp_f32_e32 v51, v51
	v_rcp_f32_e32 v55, v55
	v_add_u32_e32 v57, 0x90, v151
	v_mul_f32_e32 v56, v56, v56
; __device__ __forceinline__ unsigned cvt_pk_bf16(float lo, float hi) { unsigned r; asm volatile("v_cvt_pk_bf16_f32 %0, %1, %2" : "=v"(r) : "v"(lo), "v"(hi)); return r; }
; #define PG8_SS_DMA(u, buf) do { if constexpr (Epi::PREF) { if (wid == 0) __builtin_amdgcn_global_load_lds((const unsigned*)(E.ss + (size_t)(u).pm * BM + 4 * lane), (LAS unsigned*)(lds + STAGE_BYTES + (buf) * 1024), 16, 0, 0); } } while (0)
;     __device__ __forceinline__ void operator()(const f32x4 (&acc)[2][2][4][2], const Unit& u, int wr, int wc, int fr, int fq, const float (&sv)[8]) const {
;     ...
;             for (int m = 0; m < 4; ++m) {
;                 const int row = row0 + ai * HALF + m * 16;
;                 const float rinv = __builtin_amdgcn_rsqf(sv[ai * 4 + m] * (1.f / DM) + EPS), rneg = rinv * -1.44269504f, r2 = rinv * rinv;
;                 const f32x4 g0 = acc[ai][0][m][0], g1 = acc[ai][0][m][1], u0 = acc[ai][1][m][0], u1 = acc[ai][1][m][1];
;                 f32x4 e0, e1;
; #pragma unroll
;                 for (int j = 0; j < 4; ++j) { e0[j] = __builtin_amdgcn_rcpf(1.f + __builtin_amdgcn_exp2f(g0[j] * rneg)); e1[j] = __builtin_amdgcn_rcpf(1.f + __builtin_amdgcn_exp2f(g1[j] * rneg)); }
;                 const f32x4 a0 = (g0 * u0) * (e0 * r2), a1 = (g1 * u1) * (e1 * r2);
;                 u32x4 w;
;                 w.x = cvt_pk_bf16(a0[0], a0[1]); w.y = cvt_pk_bf16(a0[2], a0[3]); w.z = cvt_pk_bf16(a1[0], a1[1]); w.w = cvt_pk_bf16(a1[2], a1[3]);
;                 *(u32x4*)(O + (size_t)row * DFF + col0) = w;
;             }
; template <class Epi, class Sched, bool ALIGN_EPI = false, bool SP2 = false>
; __device__ __forceinline__ void gemm_phase(LAS unsigned char* lds, const Gemm g, const Sched& S, const Epi& E) {
;     ...
;         if constexpr (!Epi::AFTER_DRAIN) { E(acc, cur, wr, wc, fr, fq, sv); S.done(cur); }
;         if (!has_next) break;
; #pragma unroll
;         for (int a = 0; a < 2; ++a)
; #pragma unroll
;             for (int b = 0; b < 2; ++b)
; #pragma unroll
;                 for (int m = 0; m < 4; ++m)
; #pragma unroll
;                     for (int n = 0; n < 2; ++n) acc[a][b][m][n] = (f32x4){0.f, 0.f, 0.f, 0.f};
;         cur = nxt; cA = nA; cB = nB; ++ui;
;         PG8_SS_DMA(cur, ui & 1);
	v_add_f32_e32 v52, 1.0, v52
	v_pk_mul_f32 v[36:37], v[36:37], v[44:45]
	v_pk_mul_f32 v[44:45], v[56:57], v[48:49] op_sel_hi:[0,1]
	v_rcp_f32_e32 v52, v52
	v_rcp_f32_e32 v53, v53
	v_pk_mul_f32 v[36:37], v[36:37], v[44:45]
	v_pk_mul_f32 v[26:27], v[26:27], v[42:43]
	v_pk_mul_f32 v[24:25], v[24:25], v[40:41]
	v_pk_mul_f32 v[40:41], v[56:57], v[50:51] op_sel_hi:[0,1]
	v_pk_mul_f32 v[42:43], v[56:57], v[54:55] op_sel_hi:[0,1]
	v_pk_mul_f32 v[42:43], v[26:27], v[42:43]
	v_pk_mul_f32 v[26:27], v[24:25], v[40:41]
	v_cvt_pk_bf16_f32 v24, v36, v37
	v_fmamk_f32 v36, v140, 0x3a000000, v218
	v_rsq_f32_e32 v40, v36
	v_pk_mul_f32 v[38:39], v[38:39], v[46:47]
	v_pk_mul_f32 v[46:47], v[56:57], v[52:53] op_sel_hi:[0,1]
	v_pk_mul_f32 v[38:39], v[38:39], v[46:47]
	v_mad_i64_i32 v[36:37], s[24:25], v57, s13, v[112:113]
	v_cvt_pk_bf16_f32 v25, v38, v39
	v_cvt_pk_bf16_f32 v26, v26, v27
	v_lshl_add_u64 v[36:37], v[36:37], 0, v[114:115]
	v_mul_f32_e32 v38, 0xbfb8aa3b, v40
	v_cvt_pk_bf16_f32 v27, v42, v43
	v_mul_f32_e32 v41, v8, v38
	global_store_dwordx4 v[36:37], v[24:27], off
	v_mul_f32_e32 v39, v16, v38
	v_exp_f32_e32 v41, v41
	v_mul_f32_e32 v26, v17, v38
	v_exp_f32_e32 v27, v26
	v_mul_f32_e32 v26, v9, v38
	v_exp_f32_e32 v39, v39
	v_exp_f32_e32 v36, v26
	v_add_f32_e32 v25, 1.0, v41
	v_mul_f32_e32 v37, v10, v38
	v_add_f32_e32 v24, 1.0, v39
	v_rcp_f32_e32 v26, v25
	v_add_f32_e32 v25, 1.0, v27
	v_add_f32_e32 v27, 1.0, v36
	v_mul_f32_e32 v36, v18, v38
	v_exp_f32_e32 v37, v37
	v_mul_f32_e32 v39, v19, v38
	v_mul_f32_e32 v38, v11, v38
	v_exp_f32_e32 v39, v39
	v_exp_f32_e32 v41, v38
	v_add_f32_e32 v37, 1.0, v37
	v_rcp_f32_e32 v24, v24
	v_rcp_f32_e32 v25, v25
	v_exp_f32_e32 v36, v36
	v_rcp_f32_e32 v38, v37
	v_add_f32_e32 v37, 1.0, v39
	v_add_f32_e32 v39, 1.0, v41
	v_rcp_f32_e32 v27, v27
	v_rcp_f32_e32 v39, v39
	v_add_u32_e32 v41, 0xa0, v151
	v_mul_f32_e32 v40, v40, v40
	v_add_f32_e32 v36, 1.0, v36
	v_pk_mul_f32 v[16:17], v[16:17], v[32:33]
	v_pk_mul_f32 v[24:25], v[40:41], v[24:25] op_sel_hi:[0,1]
	v_rcp_f32_e32 v36, v36
	v_rcp_f32_e32 v37, v37
	v_pk_mul_f32 v[16:17], v[16:17], v[24:25]
	v_pk_mul_f32 v[10:11], v[10:11], v[30:31]
	v_pk_mul_f32 v[8:9], v[8:9], v[28:29]
	v_pk_mul_f32 v[24:25], v[40:41], v[26:27] op_sel_hi:[0,1]
	v_pk_mul_f32 v[26:27], v[40:41], v[38:39] op_sel_hi:[0,1]
	v_pk_mul_f32 v[26:27], v[10:11], v[26:27]
	v_pk_mul_f32 v[10:11], v[8:9], v[24:25]
	v_cvt_pk_bf16_f32 v8, v16, v17
	v_fmamk_f32 v16, v141, 0x3a000000, v218
	v_rsq_f32_e32 v24, v16
	v_pk_mul_f32 v[18:19], v[18:19], v[34:35]
	v_pk_mul_f32 v[32:33], v[40:41], v[36:37] op_sel_hi:[0,1]
	v_pk_mul_f32 v[18:19], v[18:19], v[32:33]
	v_mad_i64_i32 v[16:17], s[24:25], v41, s13, v[112:113]
	v_cvt_pk_bf16_f32 v9, v18, v19
	v_cvt_pk_bf16_f32 v10, v10, v11
	v_lshl_add_u64 v[16:17], v[16:17], 0, v[114:115]
	v_mul_f32_e32 v18, 0xbfb8aa3b, v24
	v_cvt_pk_bf16_f32 v11, v26, v27
	v_mul_f32_e32 v25, v0, v18
	global_store_dwordx4 v[16:17], v[8:11], off
	v_mul_f32_e32 v19, v4, v18
	v_exp_f32_e32 v25, v25
	v_mul_f32_e32 v10, v5, v18
	v_exp_f32_e32 v11, v10
	v_mul_f32_e32 v10, v1, v18
	v_exp_f32_e32 v19, v19
	v_exp_f32_e32 v16, v10
	v_add_f32_e32 v9, 1.0, v25
	v_mul_f32_e32 v17, v2, v18
	v_add_f32_e32 v8, 1.0, v19
	v_rcp_f32_e32 v10, v9
	v_add_f32_e32 v9, 1.0, v11
	v_add_f32_e32 v11, 1.0, v16
	v_mul_f32_e32 v16, v6, v18
	v_exp_f32_e32 v17, v17
	v_mul_f32_e32 v19, v7, v18
	v_mul_f32_e32 v18, v3, v18
	v_exp_f32_e32 v19, v19
	v_exp_f32_e32 v25, v18
	v_exp_f32_e32 v16, v16
	v_add_f32_e32 v17, 1.0, v17
	v_rcp_f32_e32 v8, v8
	v_rcp_f32_e32 v9, v9
	v_rcp_f32_e32 v18, v17
	v_add_f32_e32 v17, 1.0, v19
	v_add_f32_e32 v19, 1.0, v25
	v_rcp_f32_e32 v11, v11
	v_rcp_f32_e32 v19, v19
	v_add_f32_e32 v16, 1.0, v16
	v_rcp_f32_e32 v16, v16
	v_rcp_f32_e32 v17, v17
	v_add_u32_e32 v25, 0xb0, v151
	v_mul_f32_e32 v24, v24, v24
	v_pk_mul_f32 v[4:5], v[4:5], v[20:21]
	v_pk_mul_f32 v[8:9], v[24:25], v[8:9] op_sel_hi:[0,1]
	v_pk_mul_f32 v[4:5], v[4:5], v[8:9]
	v_pk_mul_f32 v[2:3], v[2:3], v[14:15]
	v_pk_mul_f32 v[0:1], v[0:1], v[12:13]
	v_pk_mul_f32 v[8:9], v[24:25], v[10:11] op_sel_hi:[0,1]
	v_pk_mul_f32 v[10:11], v[24:25], v[18:19] op_sel_hi:[0,1]
	v_pk_mul_f32 v[10:11], v[2:3], v[10:11]
	v_pk_mul_f32 v[2:3], v[0:1], v[8:9]
	v_cvt_pk_bf16_f32 v0, v4, v5
	v_mad_i64_i32 v[4:5], s[24:25], v25, s13, v[112:113]
	v_pk_mul_f32 v[6:7], v[6:7], v[22:23]
	v_pk_mul_f32 v[16:17], v[24:25], v[16:17] op_sel_hi:[0,1]
	v_lshl_add_u64 v[4:5], v[4:5], 0, v[114:115]
	s_andn2_b64 vcc, exec, s[36:37]
	s_mov_b64 s[24:25], -1
	v_pk_mul_f32 v[6:7], v[6:7], v[16:17]
	s_nop 0
	v_cvt_pk_bf16_f32 v1, v6, v7
	v_cvt_pk_bf16_f32 v2, v2, v3
	v_cvt_pk_bf16_f32 v3, v10, v11
	global_store_dwordx4 v[4:5], v[0:3], off
	s_cmp_lg_u32 s51, 10
	s_cbranch_scc1 .Lpa_ea_skip
	s_waitcnt vmcnt(0)
	s_barrier
	v_cmp_eq_u32_e32 vcc, 0, v216
	s_and_saveexec_b64 s[100:101], vcc
	s_cbranch_execz .Lpa_ea_done
	buffer_wbl2 sc1
	v_readlane_b32 vcc_lo, v246, 29
	s_lshl_b32 vcc_lo, vcc_lo, 6
	s_and_b32 vcc_hi, s65, 7
	s_lshl_b32 vcc_hi, vcc_hi, 2
	s_add_u32 vcc_lo, vcc_lo, vcc_hi
	s_add_u32 vcc_lo, vcc_lo, 0x83600
	v_mov_b32_e32 v2, vcc_lo
	v_mov_b32_e32 v4, 1
	s_waitcnt vmcnt(0)
	global_atomic_add v2, v4, s[98:99]
.Lpa_ea_done:
	s_or_b64 exec, exec, s[100:101]
.Lpa_ea_skip:
	s_andn2_b64 vcc, exec, s[36:37]
	s_cbranch_vccnz .LBB0_127
	s_andn2_b64 vcc, exec, s[0:1]
	s_cbranch_vccnz .LBB0_140
	s_lshl_b64 s[24:25], s[10:11], 10
	s_lshl_b32 s11, s48, 10
	s_and_b32 s11, s11, 0x400
	s_add_i32 s11, s11, 0
	v_lshl_add_u64 v[0:1], v[134:135], 0, s[24:25]
	s_add_i32 m0, s11, 0x20000
	s_nop 0
	global_load_lds_dwordx4 v[0:1], off

; template <class Epi, class Sched, bool ALIGN_EPI = false, bool SP2 = false>
; __device__ __forceinline__ void gemm_phase(LAS unsigned char* lds, const Gemm g, const Sched& S, const Epi& E) {
;     int tid = threadIdx.x; asm volatile("" : "+v"(tid));
;     const int wid = __builtin_amdgcn_readfirstlane(tid >> 6), lane = tid & 63, wr = wid >> 2, wc = wid & 3, fr = lane & 15, fq = lane >> 4;
;     const int K = g.K, nt = g.nt;
;     unsigned voffA[2], voffB[2];
; #pragma unroll
;     for (int i = 0; i < 2; ++i) { int R, C; stage_rc(tid * 16 + i * 8192, R, C); const int Rb = Epi::PERM ? ((R & ~31) + perm32(R & 31)) : R;
;         voffA[i] = (unsigned)(R * K + C) * 2u; voffB[i] = (unsigned)(Rb * K + C) * 2u; }
;     const size_t kstep = (size_t)(BK * 2);
;     const size_t hstep = (size_t)HALF * K * 2;
;     const size_t tstep = 2 * hstep;
;     const unsigned ldsw = (unsigned)wid * 1024u;
;     const int aoff = lds_byte(wr * 64 + fr, fq * 8), boff = lds_byte(wc * 32 + fr, fq * 8);
;     ...
;     Unit cur, nxt; int ui = 0;
;     if (!S.next(0, cur)) return;
;     f32x4 acc[2][2][4][2];
; #pragma unroll
;     for (int a = 0; a < 2; ++a)
; #pragma unroll
;         for (int b = 0; b < 2; ++b)
; #pragma unroll
;             for (int m = 0; m < 4; ++m)
; #pragma unroll
;                 for (int n = 0; n < 2; ++n) acc[a][b][m][n] = (f32x4){0.f, 0.f, 0.f, 0.f};
;     bf16x8 At[4][2], B0[2][2], B1[2][2];
;     const char* cA = (const char*)g.A + (size_t)cur.pm * tstep + cur.kb; const char* cB = (const char*)g.Bt + (size_t)cur.pn * tstep + cur.kb;
;     S.a_ready(cur);
;     float sv[8];
;     ...
;     PG8_SS_DMA(cur, 0);
;     if constexpr (SP2) {
;         PG8_STAGE(PG8_SB(0, 0), cB, voffB); PG8_STAGE(PG8_SB(0, 1), cB + hstep, voffB); PG8_STAGE(PG8_SA(0, 0), cA, voffA); PG8_STAGE(PG8_SA(0, 1), cA + hstep, voffA);
;         if (wr == 1) PG8_BAR;
;         PG8_WAIT_V(2); PG8_BAR;
;         PG8_STAGE(PG8_SB(1, 0), cB + kstep, voffB); PG8_STAGE(PG8_SA(1, 0), cA + kstep, voffA); PG8_STAGE(PG8_SB(1, 1), cB + hstep + kstep, voffB);
;         PG8_WAIT_V(6); PG8_BAR;
;     } else {
;         PG8_STAGE(PG8_SB(0, 0), cB, voffB); PG8_STAGE(PG8_SA(0, 0), cA, voffA); PG8_STAGE(PG8_SB(0, 1), cB + hstep, voffB); PG8_STAGE(PG8_SA(0, 1), cA + hstep, voffA);
;         if (wr == 1) PG8_BAR;
;     ...
;     PG8_WAIT_V(0);
;     if constexpr (!ALIGN_EPI) { if (wr == 0) PG8_BAR; }
;     PG8_BAR;
.LBB0_143:
	s_waitcnt vmcnt(0)
	s_waitcnt vmcnt(0) lgkmcnt(0)
	s_barrier
	v_cmp_eq_u32_e32 vcc, 0, v216
	s_and_saveexec_b64 s[100:101], vcc
	s_cbranch_execz .Lpa_gw_done
	v_readlane_b32 vcc_lo, v246, 29
	s_lshl_b32 vcc_lo, vcc_lo, 6
	s_add_u32 vcc_lo, vcc_lo, 0x83600
	s_cmpk_gt_u32 s65, 87
	s_cbranch_scc1 .Lpa_gw_poll
	buffer_wbl2 sc1
	s_add_u32 vcc_hi, vcc_lo, 32
	v_mov_b32_e32 v2, vcc_hi
	v_mov_b32_e32 v4, 1
	s_waitcnt vmcnt(0)
	global_atomic_add v2, v4, s[98:99]
.Lpa_gw_poll:
	s_and_b32 vcc_hi, s65, 7
	s_lshl_b32 vcc_hi, vcc_hi, 2
	s_add_u32 vcc_lo, vcc_lo, vcc_hi
	v_mov_b32_e32 v2, vcc_lo
	s_mov_b32 vcc_hi, 0
.Lpa_gw_loop:
	global_load_dword v3, v2, s[98:99] sc1
	s_waitcnt vmcnt(0)
	v_readfirstlane_b32 vcc_lo, v3
	s_cmpk_ge_u32 vcc_lo, 32
	s_cbranch_scc1 .Lpa_gw_acq
	s_sleep 2
	s_add_u32 vcc_hi, vcc_hi, 1
	s_cmp_lt_u32 vcc_hi, 0x100000
	s_cbranch_scc1 .Lpa_gw_loop
.Lpa_gw_acq:
	buffer_inv sc1
	s_waitcnt vmcnt(0)
.Lpa_gw_done:
	s_or_b64 exec, exec, s[100:101]
	s_and_b64 s[0:1], s[42:43], exec
	s_mov_b32 s0, 0x2c00000
	s_cselect_b32 s0, s0, 0x8700000
	v_readlane_b32 s1, v246, 30
	s_add_u32 s26, s1, s0
	v_readlane_b32 s0, v246, 31
	s_addc_u32 s27, s0, 0
	v_readlane_b32 s0, v245, 55
	v_mov_b32_e32 v5, v216
	v_readlane_b32 s1, v245, 56
	s_waitcnt lgkmcnt(0)
	s_barrier
	s_andn2_b64 vcc, exec, s[0:1]
	v_readfirstlane_b32 s0, v5
	s_cbranch_vccnz .LBB0_231
	v_lshlrev_b32_e32 v0, 4, v5
	v_add_u32_e32 v1, 0x2000, v0
	v_ashrrev_i32_e32 v2, 31, v1
	v_lshrrev_b32_e32 v2, 22, v2
	v_add_u32_e32 v2, v1, v2
	v_ashrrev_i32_e32 v4, 10, v2
	v_mul_i32_i24_e32 v2, 0x400, v4
	v_sub_u32_e32 v1, v1, v2
	v_lshrrev_b32_e32 v2, 4, v1
	v_bitop3_b32 v1, v2, v1, 32 bitop3:0x6c
	v_ashrrev_i32_e32 v2, 31, v1
	v_lshrrev_b32_e32 v2, 26, v2
	v_add_u32_e32 v2, v1, v2
	v_lshlrev_b32_e32 v3, 3, v4
	v_ashrrev_i32_e32 v6, 6, v2
	v_and_b32_e32 v3, -16, v3
	v_add_u32_e32 v3, v6, v3
	v_and_b32_e32 v7, 3, v6
	s_mov_b32 s4, 0x7fffe0
	v_lshrrev_b32_e32 v8, 2, v3
	v_lshlrev_b32_e32 v9, 1, v3
	v_and_or_b32 v7, v3, s4, v7
	v_and_b32_e32 v8, 4, v8
	v_and_b32_e32 v9, 24, v9
	v_and_b32_e32 v2, 0xc0, v2
	v_or3_b32 v7, v7, v8, v9
	v_sub_u32_e32 v1, v1, v2
	v_mul_u32_u24_e32 v9, 0x1600, v7
	v_lshlrev_b32_e32 v7, 5, v4
	v_ashrrev_i16_sdwa v1, v219, sext(v1) dst_sel:DWORD dst_unused:UNUSED_PAD src0_sel:DWORD src1_sel:BYTE_0
	v_and_b32_e32 v7, 32, v7
	v_bfe_i32 v8, v1, 0, 16
	s_movk_i32 s5, 0x1600
	v_add_u32_e32 v1, v7, v8
	v_mul_lo_u32 v2, v3, s5
	v_add_lshl_u32 v202, v9, v1, 1
	v_add_lshl_u32 v204, v1, v2, 1
	v_bfe_i32 v1, v5, 27, 1
	v_lshrrev_b32_e32 v1, 22, v1
	v_add_u32_e32 v1, v0, v1
	v_and_b32_e32 v1, 0xfffffc00, v1
	v_sub_u32_e32 v0, v0, v1
	v_lshrrev_b32_e32 v1, 4, v0
	v_ashrrev_i32_e32 v2, 31, v5
	v_bitop3_b32 v0, v1, v0, 32 bitop3:0x6c
	v_lshrrev_b32_e32 v2, 26, v2
	v_ashrrev_i32_e32 v1, 31, v0
	v_add_u32_e32 v2, v5, v2
	v_lshrrev_b32_e32 v1, 26, v1
	v_ashrrev_i32_e32 v10, 6, v2
	v_add_u32_e32 v1, v0, v1
	v_lshlrev_b32_e32 v2, 3, v10
	v_ashrrev_i32_e32 v9, 6, v1
	v_and_b32_e32 v2, -16, v2
	v_add_u32_e32 v2, v9, v2
	v_and_b32_e32 v3, 3, v9
	v_lshrrev_b32_e32 v11, 2, v2
	v_lshlrev_b32_e32 v12, 1, v2
	v_and_b32_e32 v1, 0xc0, v1
	s_ashr_i32 s8, s0, 6
	v_and_or_b32 v3, v2, s4, v3
	v_and_b32_e32 v11, 4, v11
	v_and_b32_e32 v12, 24, v12
	v_sub_u32_e32 v0, v0, v1
	s_ashr_i32 s1, s0, 8
	s_lshl_b32 s28, s8, 10
	v_or3_b32 v3, v3, v11, v12
	v_lshlrev_b32_e32 v11, 5, v10
	v_ashrrev_i16_sdwa v0, v219, sext(v0) dst_sel:DWORD dst_unused:UNUSED_PAD src0_sel:DWORD src1_sel:BYTE_0
	v_readlane_b32 s4, v244, 30
	v_and_b32_e32 v11, 32, v11
	v_bfe_i32 v12, v0, 0, 16
	s_add_u32 s16, s26, s4
	v_readlane_b32 s4, v244, 31
	v_mul_u32_u24_e32 v3, 0x1600, v3
	v_add_u32_e32 v0, v11, v12
	s_addc_u32 s17, s27, s4
	s_add_i32 s29, s28, 0
	v_add_lshl_u32 v188, v3, v0, 1
	s_add_i32 m0, s29, 0x10000
	v_mul_lo_u32 v1, v2, s5
	global_load_lds_dwordx4 v188, s[16:17]
	s_add_i32 m0, s29, 0x12000
	s_add_u32 s4, s16, 0x160000
	global_load_lds_dwordx4 v202, s[16:17]
	s_addc_u32 s5, s17, 0
	s_add_i32 m0, s29, 0x14000
	v_add_lshl_u32 v206, v0, v1, 1
	global_load_lds_dwordx4 v188, s[4:5]
	s_add_i32 m0, s29, 0x16000
	s_add_i32 s31, s29, 0x2000
	global_load_lds_dwordx4 v202, s[4:5]
	v_readlane_b32 s4, v244, 32
	s_mov_b32 m0, s29
	v_readlane_b32 s5, v244, 33
	s_add_i32 s34, s29, 0x4000
	s_add_i32 s35, s29, 0x6000
	v_mov_b32_e32 v203, v189
	s_cmp_eq_u32 s1, 1
	v_lshl_add_u64 v[0:1], s[16:17], 0, v[188:189]
	global_load_lds_dwordx4 v206, s[4:5]
	s_mov_b32 m0, s31
	v_lshl_add_u64 v[2:3], s[16:17], 0, v[202:203]
	global_load_lds_dwordx4 v204, s[4:5]
	v_readlane_b32 s4, v244, 34
	s_mov_b32 m0, s34
	v_readlane_b32 s5, v244, 35
	s_nop 4
	global_load_lds_dwordx4 v206, s[4:5]
	s_mov_b32 m0, s35
	s_nop 0
	global_load_lds_dwordx4 v204, s[4:5]
	s_cselect_b64 s[4:5], -1, 0
	s_cmp_lg_u32 s1, 1
	s_cbranch_scc1 .LBB0_195
	s_barrier

; #define PG8_WAIT_V(n) asm volatile("s_waitcnt vmcnt(" #n ")" ::: "memory")
; template <class Epi, class Sched, bool ALIGN_EPI = false, bool SP2 = false>
; __device__ __forceinline__ void gemm_phase(LAS unsigned char* lds, const Gemm g, const Sched& S, const Epi& E) {
;     int tid = threadIdx.x; asm volatile("" : "+v"(tid));
;     const int wid = __builtin_amdgcn_readfirstlane(tid >> 6), lane = tid & 63, wr = wid >> 2, wc = wid & 3, fr = lane & 15, fq = lane >> 4;
;     const int K = g.K, nt = g.nt;
;     unsigned voffA[2], voffB[2];
; #pragma unroll
;     for (int i = 0; i < 2; ++i) { int R, C; stage_rc(tid * 16 + i * 8192, R, C); const int Rb = Epi::PERM ? ((R & ~31) + perm32(R & 31)) : R;
;         voffA[i] = (unsigned)(R * K + C) * 2u; voffB[i] = (unsigned)(Rb * K + C) * 2u; }
;     const size_t kstep = (size_t)(BK * 2);
;     const size_t hstep = (size_t)HALF * K * 2;
;     const size_t tstep = 2 * hstep;
;     const unsigned ldsw = (unsigned)wid * 1024u;
;     const int aoff = lds_byte(wr * 64 + fr, fq * 8), boff = lds_byte(wc * 32 + fr, fq * 8);
;     ...
;     Unit cur, nxt; int ui = 0;
;     if (!S.next(0, cur)) return;
;     f32x4 acc[2][2][4][2];
; #pragma unroll
;     for (int a = 0; a < 2; ++a)
; #pragma unroll
;         for (int b = 0; b < 2; ++b)
; #pragma unroll
;             for (int m = 0; m < 4; ++m)
; #pragma unroll
;                 for (int n = 0; n < 2; ++n) acc[a][b][m][n] = (f32x4){0.f, 0.f, 0.f, 0.f};
;     bf16x8 At[4][2], B0[2][2], B1[2][2];
;     const char* cA = (const char*)g.A + (size_t)cur.pm * tstep + cur.kb; const char* cB = (const char*)g.Bt + (size_t)cur.pn * tstep + cur.kb;
;     S.a_ready(cur);
;     float sv[8];
;     ...
;     PG8_SS_DMA(cur, 0);
;     if constexpr (SP2) {
;         PG8_STAGE(PG8_SB(0, 0), cB, voffB); PG8_STAGE(PG8_SB(0, 1), cB + hstep, voffB); PG8_STAGE(PG8_SA(0, 0), cA, voffA); PG8_STAGE(PG8_SA(0, 1), cA + hstep, voffA);
;         if (wr == 1) PG8_BAR;
;         PG8_WAIT_V(2); PG8_BAR;
;         PG8_STAGE(PG8_SB(1, 0), cB + kstep, voffB); PG8_STAGE(PG8_SA(1, 0), cA + kstep, voffA); PG8_STAGE(PG8_SB(1, 1), cB + hstep + kstep, voffB);
;         PG8_WAIT_V(6); PG8_BAR;
;     } else {
;         PG8_STAGE(PG8_SB(0, 0), cB, voffB); PG8_STAGE(PG8_SA(0, 0), cA, voffA); PG8_STAGE(PG8_SB(0, 1), cB + hstep, voffB); PG8_STAGE(PG8_SA(0, 1), cA + hstep, voffA);
;         if (wr == 1) PG8_BAR;
;         PG8_WAIT_V(4); PG8_BAR;
.LBB0_231:
	v_readlane_b32 s0, v245, 57
	v_mov_b32_e32 v8, v216
	v_readlane_b32 s1, v245, 58
	s_andn2_b64 vcc, exec, s[0:1]
	v_readfirstlane_b32 s16, v8
	s_cbranch_vccnz .LBB0_239
	v_readlane_b32 s100, v246, 29
	s_lshl_b32 s100, s100, 6
	s_add_u32 s100, s100, 0x83620
	v_mov_b32_e32 v0, s100
	s_mov_b32 s101, 0
.Lpa_sw_loop:
	global_load_dword v1, v0, s[98:99] sc1
	s_waitcnt vmcnt(0)
	v_readfirstlane_b32 s100, v1
	s_cmpk_ge_u32 s100, 88
	s_cbranch_scc1 .Lpa_sw_acq
	s_sleep 2
	s_add_u32 s101, s101, 1
	s_cmp_lt_u32 s101, 0x100000
	s_cbranch_scc1 .Lpa_sw_loop
.Lpa_sw_acq:
	buffer_inv sc1
	s_waitcnt vmcnt(0)
	v_lshlrev_b32_e32 v0, 4, v8
	s_waitcnt lgkmcnt(0)
	v_add_u32_e32 v1, 0x2000, v0
	v_ashrrev_i32_e32 v2, 31, v1
	v_lshrrev_b32_e32 v2, 22, v2
	v_add_u32_e32 v2, v1, v2
	v_ashrrev_i32_e32 v4, 10, v2
	v_mul_i32_i24_e32 v2, 0x400, v4
	v_sub_u32_e32 v1, v1, v2
	v_lshrrev_b32_e32 v2, 4, v1
	v_bitop3_b32 v1, v2, v1, 32 bitop3:0x6c
	v_ashrrev_i32_e32 v2, 31, v1
	v_lshrrev_b32_e32 v2, 26, v2
	v_add_u32_e32 v2, v1, v2
	v_lshlrev_b32_e32 v3, 3, v4
	v_ashrrev_i32_e32 v5, 6, v2
	v_and_b32_e32 v3, -16, v3
	v_add_u32_e32 v3, v5, v3
	v_and_b32_e32 v6, 3, v5
	s_mov_b32 s0, 0x7fffe0
	v_lshrrev_b32_e32 v7, 2, v3
	v_lshlrev_b32_e32 v9, 1, v3
	v_and_or_b32 v6, v3, s0, v6
	v_and_b32_e32 v7, 4, v7
	v_and_b32_e32 v9, 24, v9
	v_and_b32_e32 v2, 0xc0, v2
	v_or3_b32 v6, v6, v7, v9
	v_sub_u32_e32 v1, v1, v2
	v_mul_u32_u24_e32 v9, 0x1600, v6
	v_lshlrev_b32_e32 v6, 5, v4
	v_ashrrev_i16_sdwa v1, v219, sext(v1) dst_sel:DWORD dst_unused:UNUSED_PAD src0_sel:DWORD src1_sel:BYTE_0
	v_and_b32_e32 v6, 32, v6
	v_bfe_i32 v7, v1, 0, 16
	s_movk_i32 s1, 0x1600
	v_add_u32_e32 v1, v6, v7
	v_mul_lo_u32 v2, v3, s1
	v_add_lshl_u32 v128, v9, v1, 1
	v_add_lshl_u32 v130, v1, v2, 1
	v_bfe_i32 v1, v8, 27, 1
	v_lshrrev_b32_e32 v1, 22, v1
	v_add_u32_e32 v1, v0, v1
	v_and_b32_e32 v1, 0xfffffc00, v1
	v_sub_u32_e32 v0, v0, v1
	v_lshrrev_b32_e32 v1, 4, v0
	v_ashrrev_i32_e32 v2, 31, v8
	v_bitop3_b32 v0, v1, v0, 32 bitop3:0x6c
	v_lshrrev_b32_e32 v2, 26, v2
	v_ashrrev_i32_e32 v1, 31, v0
	v_add_u32_e32 v2, v8, v2
	v_lshrrev_b32_e32 v1, 26, v1
	v_ashrrev_i32_e32 v10, 6, v2
	v_add_u32_e32 v1, v0, v1
	v_lshlrev_b32_e32 v2, 3, v10
	v_ashrrev_i32_e32 v9, 6, v1
	v_and_b32_e32 v2, -16, v2
	s_ashr_i32 s4, s16, 6
	v_add_u32_e32 v2, v9, v2
	v_and_b32_e32 v3, 3, v9
	s_ashr_i32 s5, s16, 8
	s_lshl_b32 s17, s4, 10
	v_and_or_b32 v3, v2, s0, v3
	v_lshrrev_b32_e32 v11, 2, v2
	v_lshlrev_b32_e32 v12, 1, v2
	v_and_b32_e32 v1, 0xc0, v1
	v_readlane_b32 s0, v246, 12
	v_and_b32_e32 v11, 4, v11
	v_and_b32_e32 v12, 24, v12
	v_sub_u32_e32 v0, v0, v1
	s_add_u32 s0, s26, s0
	v_or3_b32 v3, v3, v11, v12
	v_lshlrev_b32_e32 v11, 5, v10
	v_ashrrev_i16_sdwa v0, v219, sext(v0) dst_sel:DWORD dst_unused:UNUSED_PAD src0_sel:DWORD src1_sel:BYTE_0
	v_mul_lo_u32 v1, v2, s1
	s_addc_u32 s1, s27, 0
	v_readlane_b32 s8, v244, 59
	v_and_b32_e32 v11, 32, v11
	v_bfe_i32 v12, v0, 0, 16
	s_add_u32 s0, s0, s8
	v_readlane_b32 s8, v244, 60
	v_mul_u32_u24_e32 v3, 0x1600, v3
	v_add_u32_e32 v0, v11, v12
	s_addc_u32 s1, s1, s8
	s_add_i32 s22, s17, 0
	v_add_lshl_u32 v188, v3, v0, 1
	s_add_i32 m0, s22, 0x10000
	v_readlane_b32 s36, v245, 59
	global_load_lds_dwordx4 v188, s[0:1]
	s_add_i32 m0, s22, 0x12000
	s_add_u32 s8, s0, 0x160000
	global_load_lds_dwordx4 v128, s[0:1]
	s_addc_u32 s9, s1, 0
	s_add_i32 m0, s22, 0x14000
	v_add_lshl_u32 v132, v0, v1, 1
	global_load_lds_dwordx4 v188, s[8:9]
	s_add_i32 m0, s22, 0x16000
	v_readlane_b32 s37, v245, 60
	global_load_lds_dwordx4 v128, s[8:9]
	s_mov_b32 m0, s22
	s_add_i32 s23, s22, 0x2000
	s_add_i32 s24, s22, 0x4000
	s_nop 0
	global_load_lds_dwordx4 v132, s[36:37]
	s_mov_b32 m0, s23
	v_readlane_b32 s8, v245, 61
	global_load_lds_dwordx4 v130, s[36:37]
	s_mov_b32 m0, s24
	v_readlane_b32 s9, v245, 62
	s_add_i32 s25, s22, 0x6000
	v_mov_b32_e32 v129, v189
	v_lshl_add_u64 v[0:1], s[0:1], 0, v[188:189]
	s_cmp_lg_u32 s5, 1
	v_lshl_add_u64 v[2:3], s[0:1], 0, v[128:129]
	global_load_lds_dwordx4 v132, s[8:9]
	s_mov_b32 m0, s25
	s_nop 0
	global_load_lds_dwordx4 v130, s[8:9]
	s_cbranch_scc1 .LBB0_234
	s_barrier

; __global__ void __launch_bounds__(512, 2) fwd_megakernel(Params p) {
	.amdhsa_kernel _Z14fwd_megakernel6Params
		.amdhsa_group_segment_fixed_size 0
		.amdhsa_private_segment_fixed_size 0
		.amdhsa_kernarg_size 464
		.amdhsa_user_sgpr_count 2
		.amdhsa_user_sgpr_dispatch_ptr 0
		.amdhsa_user_sgpr_queue_ptr 0
		.amdhsa_user_sgpr_kernarg_segment_ptr 1
		.amdhsa_user_sgpr_dispatch_id 0
		.amdhsa_user_sgpr_kernarg_preload_length 0
		.amdhsa_user_sgpr_kernarg_preload_offset 0
		.amdhsa_user_sgpr_private_segment_size 0
		.amdhsa_uses_dynamic_stack 0
		.amdhsa_enable_private_segment 0
		.amdhsa_system_sgpr_workgroup_id_x 1
		.amdhsa_system_sgpr_workgroup_id_y 0
		.amdhsa_system_sgpr_workgroup_id_z 0
		.amdhsa_system_sgpr_workgroup_info 0
		.amdhsa_system_vgpr_workitem_id 2
		.amdhsa_next_free_vgpr 248
		.amdhsa_next_free_sgpr 102
		.amdhsa_accum_offset 248
		.amdhsa_reserve_vcc 1
		.amdhsa_float_round_mode_32 0
		.amdhsa_float_round_mode_16_64 0
		.amdhsa_float_denorm_mode_32 3
		.amdhsa_float_denorm_mode_16_64 3
		.amdhsa_dx10_clamp 1
		.amdhsa_ieee_mode 1
		.amdhsa_fp16_overflow 0
		.amdhsa_tg_split 0
		.amdhsa_exception_fp_ieee_invalid_op 0
		.amdhsa_exception_fp_denorm_src 0
		.amdhsa_exception_fp_ieee_div_zero 0
		.amdhsa_exception_fp_ieee_overflow 0
		.amdhsa_exception_fp_ieee_underflow 0
		.amdhsa_exception_fp_ieee_inexact 0
		.amdhsa_exception_int_div_zero 0
	.end_amdhsa_kernel

; __global__ void __launch_bounds__(512, 2) fwd_megakernel(Params p) {
.Lfunc_end0:
	.size	_Z14fwd_megakernel6Params, .Lfunc_end0-_Z14fwd_megakernel6Params
	.set _Z14fwd_megakernel6Params.num_vgpr, 248
	.set _Z14fwd_megakernel6Params.num_agpr, 0
	.set _Z14fwd_megakernel6Params.numbered_sgpr, 102
	.set _Z14fwd_megakernel6Params.num_named_barrier, 0
	.set _Z14fwd_megakernel6Params.private_seg_size, 0
	.set _Z14fwd_megakernel6Params.uses_vcc, 1
	.set _Z14fwd_megakernel6Params.uses_flat_scratch, 0
	.set _Z14fwd_megakernel6Params.has_dyn_sized_stack, 0
	.set _Z14fwd_megakernel6Params.has_recursion, 0
	.set _Z14fwd_megakernel6Params.has_indirect_call, 0

; __global__ void __launch_bounds__(512, 2) fwd_megakernel(Params p) {
amdhsa.kernels:
  - .agpr_count:     0
    .args:
      - .offset:         0
        .size:           208
        .value_kind:     by_value
      - .offset:         208
        .size:           4
        .value_kind:     hidden_block_count_x
      - .offset:         212
        .size:           4
        .value_kind:     hidden_block_count_y
      - .offset:         216
        .size:           4
        .value_kind:     hidden_block_count_z
      - .offset:         220
        .size:           2
        .value_kind:     hidden_group_size_x
      - .offset:         222
        .size:           2
        .value_kind:     hidden_group_size_y
      - .offset:         224
        .size:           2
        .value_kind:     hidden_group_size_z
      - .offset:         226
        .size:           2
        .value_kind:     hidden_remainder_x
      - .offset:         228
        .size:           2
        .value_kind:     hidden_remainder_y
      - .offset:         230
        .size:           2
        .value_kind:     hidden_remainder_z
      - .offset:         248
        .size:           8
        .value_kind:     hidden_global_offset_x
      - .offset:         256
        .size:           8
        .value_kind:     hidden_global_offset_y
      - .offset:         264
        .size:           8
        .value_kind:     hidden_global_offset_z
      - .offset:         272
        .size:           2
        .value_kind:     hidden_grid_dims
      - .offset:         296
        .size:           8
        .value_kind:     hidden_multigrid_sync_arg
      - .offset:         328
        .size:           4
        .value_kind:     hidden_dynamic_lds_size
    .group_segment_fixed_size: 0
    .kernarg_segment_align: 8
    .kernarg_segment_size: 464
    .language:       OpenCL C
    .language_version:
      - 2
      - 0
    .max_flat_workgroup_size: 512
    .name:           _Z14fwd_megakernel6Params
    .private_segment_fixed_size: 0
    .sgpr_count:     108
    .sgpr_spill_count: 240
    .symbol:         _Z14fwd_megakernel6Params.kd
    .uniform_work_group_size: 1
    .uses_dynamic_stack: false
    .vgpr_count:     248
    .vgpr_spill_count: 0
    .wavefront_size: 64
